# EpiResid epilogue rewritten by hand on top of v1: 16 hb loads hoisted, stores not waited, partial-sum shuffles batched
# baseline (speedup 1.0000x reference)
; __device__ __forceinline__ unsigned cvt_pk_bf16(float lo, float hi) { unsigned r; asm volatile("v_cvt_pk_bf16_f32 %0, %1, %2" : "=v"(r) : "v"(lo), "v"(hi)); return r; }
;     __device__ __forceinline__ void operator()(const f32x4 (&acc)[2][2][4][2], const Unit& u, int wr, int wc, int fr, int fq) const {
;         const int row0 = u.pm * BM + wr * 64 + fr, col0 = u.pn * BM + wc * 32 + 8 * fq;
; #pragma unroll
;         for (int ai = 0; ai < 2; ++ai)
; #pragma unroll
;             for (int m = 0; m < 4; ++m) { const int row = row0 + ai * HALF + m * 16; const size_t off = (size_t)row * 1024 + col0; float part = 0.f;
; #pragma unroll
;                 for (int bj = 0; bj < 2; ++bj) { const u32x4 b = *(const u32x4*)(hb + off + bj * HALF);
;                     f32x4 v0 = acc[ai][bj][m][0], v1 = acc[ai][bj][m][1];
;                     v0[0] += __uint_as_float(b.x << 16); v0[1] += __uint_as_float(b.x & 0xffff0000u); v0[2] += __uint_as_float(b.y << 16); v0[3] += __uint_as_float(b.y & 0xffff0000u);
;                     v1[0] += __uint_as_float(b.z << 16); v1[1] += __uint_as_float(b.z & 0xffff0000u); v1[2] += __uint_as_float(b.w << 16); v1[3] += __uint_as_float(b.w & 0xffff0000u);
;                     u32x4 w; w.x = cvt_pk_bf16(v0[0], v0[1]); w.y = cvt_pk_bf16(v0[2], v0[3]); w.z = cvt_pk_bf16(v1[0], v1[1]); w.w = cvt_pk_bf16(v1[2], v1[3]);
;                     *(u32x4*)(hb + off + bj * HALF) = w;
;                     part += (v0[0] * v0[0] + v0[1] * v0[1]) + (v0[2] * v0[2] + v0[3] * v0[3]) + (v1[0] * v1[0] + v1[1] * v1[1]) + (v1[2] * v1[2] + v1[3] * v1[3]); }
;                 part += __shfl_xor(part, 16); part += __shfl_xor(part, 32);
;                 if (fq == 0) ssq[(size_t)row * 16 + u.pn * 4 + wc] = part; }
;     }
.LBB0_641:
	v_lshl_add_u32 v238, s53, 8, v146
	v_lshl_or_b32 v239, s11, 8, v148
	v_lshlrev_b32_e32 v239, 1, v239
	v_lshl_add_u32 v142, v238, 11, v239
	v_add_u32_e32 v143, 0x8000, v142
	v_add_u32_e32 v144, 0x8000, v143
	v_add_u32_e32 v145, 0x8000, v144
	v_add_u32_e32 v204, 0x40000, v142
	v_add_u32_e32 v205, 0x40000, v143
	v_add_u32_e32 v206, 0x40000, v144
	v_add_u32_e32 v207, 0x40000, v145
	global_load_dwordx4 v[150:153], v142, s[8:9]
	global_load_dwordx4 v[154:157], v142, s[8:9] offset:256
	global_load_dwordx4 v[158:161], v143, s[8:9]
	global_load_dwordx4 v[162:165], v143, s[8:9] offset:256
	global_load_dwordx4 v[166:169], v144, s[8:9]
	global_load_dwordx4 v[170:173], v144, s[8:9] offset:256
	global_load_dwordx4 v[174:177], v145, s[8:9]
	global_load_dwordx4 v[178:181], v145, s[8:9] offset:256
	global_load_dwordx4 v[182:185], v204, s[8:9]
	global_load_dwordx4 v[186:189], v204, s[8:9] offset:256
	global_load_dwordx4 v[190:193], v205, s[8:9]
	global_load_dwordx4 v[194:197], v205, s[8:9] offset:256
	global_load_dwordx4 v[220:223], v206, s[8:9]
	global_load_dwordx4 v[224:227], v206, s[8:9] offset:256
	global_load_dwordx4 v[228:231], v207, s[8:9]
	global_load_dwordx4 v[232:235], v207, s[8:9] offset:256
	v_xor_b32_e32 v236, 16, v214
	v_lshlrev_b32_e32 v236, 2, v236
	v_xor_b32_e32 v237, 32, v214
	v_lshlrev_b32_e32 v237, 2, v237
	s_waitcnt vmcnt(14)
	v_lshlrev_b32_e32 v239, 16, v150
	v_and_b32_e32 v240, 0xffff0000, v150
	v_add_f32_e32 v128, v128, v239
	v_add_f32_e32 v129, v129, v240
	v_lshlrev_b32_e32 v239, 16, v151
	v_and_b32_e32 v240, 0xffff0000, v151
	v_add_f32_e32 v130, v130, v239
	v_add_f32_e32 v131, v131, v240
	v_lshlrev_b32_e32 v239, 16, v152
	v_and_b32_e32 v240, 0xffff0000, v152
	v_add_f32_e32 v124, v124, v239
	v_add_f32_e32 v125, v125, v240
	v_lshlrev_b32_e32 v239, 16, v153
	v_and_b32_e32 v240, 0xffff0000, v153
	v_add_f32_e32 v126, v126, v239
	v_add_f32_e32 v127, v127, v240
	v_cvt_pk_bf16_f32 v150, v128, v129
	v_cvt_pk_bf16_f32 v151, v130, v131
	v_cvt_pk_bf16_f32 v152, v124, v125
	v_cvt_pk_bf16_f32 v153, v126, v127
	global_store_dwordx4 v142, v[150:153], s[8:9]
	v_mul_f32_e32 v239, v129, v129
	v_mul_f32_e32 v240, v131, v131
	v_fmac_f32_e32 v239, v128, v128
	v_fmac_f32_e32 v240, v130, v130
	v_add_f32_e32 v239, v239, v240
	v_mul_f32_e32 v240, v125, v125
	v_fmac_f32_e32 v240, v124, v124
	v_add_f32_e32 v239, v240, v239
	v_mul_f32_e32 v240, v127, v127
	v_fmac_f32_e32 v240, v126, v126
	v_add_f32_e32 v128, v240, v239
	v_lshlrev_b32_e32 v239, 16, v154
	v_and_b32_e32 v240, 0xffff0000, v154
	v_add_f32_e32 v120, v120, v239
	v_add_f32_e32 v121, v121, v240
	v_lshlrev_b32_e32 v239, 16, v155
	v_and_b32_e32 v240, 0xffff0000, v155
	v_add_f32_e32 v122, v122, v239
	v_add_f32_e32 v123, v123, v240
	v_lshlrev_b32_e32 v239, 16, v156
	v_and_b32_e32 v240, 0xffff0000, v156
	v_add_f32_e32 v116, v116, v239
	v_add_f32_e32 v117, v117, v240
	v_lshlrev_b32_e32 v239, 16, v157
	v_and_b32_e32 v240, 0xffff0000, v157
	v_add_f32_e32 v118, v118, v239
	v_add_f32_e32 v119, v119, v240
	v_cvt_pk_bf16_f32 v154, v120, v121
	v_cvt_pk_bf16_f32 v155, v122, v123
	v_cvt_pk_bf16_f32 v156, v116, v117
	v_cvt_pk_bf16_f32 v157, v118, v119
	global_store_dwordx4 v142, v[154:157], s[8:9] offset:256
	v_mul_f32_e32 v239, v121, v121
	v_mul_f32_e32 v240, v123, v123
	v_fmac_f32_e32 v239, v120, v120
	v_fmac_f32_e32 v240, v122, v122
	v_add_f32_e32 v239, v239, v240
	v_mul_f32_e32 v240, v117, v117
	v_fmac_f32_e32 v240, v116, v116
	v_add_f32_e32 v239, v240, v239
	v_mul_f32_e32 v240, v119, v119
	v_fmac_f32_e32 v240, v118, v118
	v_add_f32_e32 v120, v240, v239
	v_add_f32_e32 v128, v128, v120
	s_waitcnt vmcnt(14)
	v_lshlrev_b32_e32 v239, 16, v158
	v_and_b32_e32 v240, 0xffff0000, v158
	v_add_f32_e32 v112, v112, v239
	v_add_f32_e32 v113, v113, v240
	v_lshlrev_b32_e32 v239, 16, v159
	v_and_b32_e32 v240, 0xffff0000, v159
	v_add_f32_e32 v114, v114, v239
	v_add_f32_e32 v115, v115, v240
	v_lshlrev_b32_e32 v239, 16, v160
	v_and_b32_e32 v240, 0xffff0000, v160
	v_add_f32_e32 v108, v108, v239
	v_add_f32_e32 v109, v109, v240
	v_lshlrev_b32_e32 v239, 16, v161
	v_and_b32_e32 v240, 0xffff0000, v161
	v_add_f32_e32 v110, v110, v239
	v_add_f32_e32 v111, v111, v240
	v_cvt_pk_bf16_f32 v158, v112, v113
	v_cvt_pk_bf16_f32 v159, v114, v115
	v_cvt_pk_bf16_f32 v160, v108, v109
	v_cvt_pk_bf16_f32 v161, v110, v111
	global_store_dwordx4 v143, v[158:161], s[8:9]
	v_mul_f32_e32 v239, v113, v113
	v_mul_f32_e32 v240, v115, v115
	v_fmac_f32_e32 v239, v112, v112
	v_fmac_f32_e32 v240, v114, v114
	v_add_f32_e32 v239, v239, v240
	v_mul_f32_e32 v240, v109, v109
	v_fmac_f32_e32 v240, v108, v108
	v_add_f32_e32 v239, v240, v239
	v_mul_f32_e32 v240, v111, v111
	v_fmac_f32_e32 v240, v110, v110
	v_add_f32_e32 v112, v240, v239
	v_lshlrev_b32_e32 v239, 16, v162
	v_and_b32_e32 v240, 0xffff0000, v162
	v_add_f32_e32 v104, v104, v239
	v_add_f32_e32 v105, v105, v240
	v_lshlrev_b32_e32 v239, 16, v163
	v_and_b32_e32 v240, 0xffff0000, v163
	v_add_f32_e32 v106, v106, v239
	v_add_f32_e32 v107, v107, v240
	v_lshlrev_b32_e32 v239, 16, v164
	v_and_b32_e32 v240, 0xffff0000, v164
	v_add_f32_e32 v100, v100, v239
	v_add_f32_e32 v101, v101, v240
	v_lshlrev_b32_e32 v239, 16, v165
	v_and_b32_e32 v240, 0xffff0000, v165
	v_add_f32_e32 v102, v102, v239
	v_add_f32_e32 v103, v103, v240
	v_cvt_pk_bf16_f32 v162, v104, v105
	v_cvt_pk_bf16_f32 v163, v106, v107
	v_cvt_pk_bf16_f32 v164, v100, v101
	v_cvt_pk_bf16_f32 v165, v102, v103
	global_store_dwordx4 v143, v[162:165], s[8:9] offset:256
	v_mul_f32_e32 v239, v105, v105
	v_mul_f32_e32 v240, v107, v107
	v_fmac_f32_e32 v239, v104, v104
	v_fmac_f32_e32 v240, v106, v106
	v_add_f32_e32 v239, v239, v240
	v_mul_f32_e32 v240, v101, v101
	v_fmac_f32_e32 v240, v100, v100
	v_add_f32_e32 v239, v240, v239
	v_mul_f32_e32 v240, v103, v103
	v_fmac_f32_e32 v240, v102, v102
	v_add_f32_e32 v104, v240, v239
	v_add_f32_e32 v112, v112, v104
	s_waitcnt vmcnt(14)
; __device__ __forceinline__ unsigned cvt_pk_bf16(float lo, float hi) { unsigned r; asm volatile("v_cvt_pk_bf16_f32 %0, %1, %2" : "=v"(r) : "v"(lo), "v"(hi)); return r; }
;     __device__ __forceinline__ void operator()(const f32x4 (&acc)[2][2][4][2], const Unit& u, int wr, int wc, int fr, int fq) const {
;     ...
;             for (int m = 0; m < 4; ++m) { const int row = row0 + ai * HALF + m * 16; const size_t off = (size_t)row * 1024 + col0; float part = 0.f;
; #pragma unroll
;                 for (int bj = 0; bj < 2; ++bj) { const u32x4 b = *(const u32x4*)(hb + off + bj * HALF);
;                     f32x4 v0 = acc[ai][bj][m][0], v1 = acc[ai][bj][m][1];
;                     v0[0] += __uint_as_float(b.x << 16); v0[1] += __uint_as_float(b.x & 0xffff0000u); v0[2] += __uint_as_float(b.y << 16); v0[3] += __uint_as_float(b.y & 0xffff0000u);
;                     v1[0] += __uint_as_float(b.z << 16); v1[1] += __uint_as_float(b.z & 0xffff0000u); v1[2] += __uint_as_float(b.w << 16); v1[3] += __uint_as_float(b.w & 0xffff0000u);
;                     u32x4 w; w.x = cvt_pk_bf16(v0[0], v0[1]); w.y = cvt_pk_bf16(v0[2], v0[3]); w.z = cvt_pk_bf16(v1[0], v1[1]); w.w = cvt_pk_bf16(v1[2], v1[3]);
;                     *(u32x4*)(hb + off + bj * HALF) = w;
;                     part += (v0[0] * v0[0] + v0[1] * v0[1]) + (v0[2] * v0[2] + v0[3] * v0[3]) + (v1[0] * v1[0] + v1[1] * v1[1]) + (v1[2] * v1[2] + v1[3] * v1[3]); }
	v_lshlrev_b32_e32 v239, 16, v166
	v_and_b32_e32 v240, 0xffff0000, v166
	v_add_f32_e32 v96, v96, v239
	v_add_f32_e32 v97, v97, v240
	v_lshlrev_b32_e32 v239, 16, v167
	v_and_b32_e32 v240, 0xffff0000, v167
	v_add_f32_e32 v98, v98, v239
	v_add_f32_e32 v99, v99, v240
	v_lshlrev_b32_e32 v239, 16, v168
	v_and_b32_e32 v240, 0xffff0000, v168
	v_add_f32_e32 v92, v92, v239
	v_add_f32_e32 v93, v93, v240
	v_lshlrev_b32_e32 v239, 16, v169
	v_and_b32_e32 v240, 0xffff0000, v169
	v_add_f32_e32 v94, v94, v239
	v_add_f32_e32 v95, v95, v240
	v_cvt_pk_bf16_f32 v166, v96, v97
	v_cvt_pk_bf16_f32 v167, v98, v99
	v_cvt_pk_bf16_f32 v168, v92, v93
	v_cvt_pk_bf16_f32 v169, v94, v95
	global_store_dwordx4 v144, v[166:169], s[8:9]
	v_mul_f32_e32 v239, v97, v97
	v_mul_f32_e32 v240, v99, v99
	v_fmac_f32_e32 v239, v96, v96
	v_fmac_f32_e32 v240, v98, v98
	v_add_f32_e32 v239, v239, v240
	v_mul_f32_e32 v240, v93, v93
	v_fmac_f32_e32 v240, v92, v92
	v_add_f32_e32 v239, v240, v239
	v_mul_f32_e32 v240, v95, v95
	v_fmac_f32_e32 v240, v94, v94
	v_add_f32_e32 v96, v240, v239
	v_lshlrev_b32_e32 v239, 16, v170
	v_and_b32_e32 v240, 0xffff0000, v170
	v_add_f32_e32 v88, v88, v239
	v_add_f32_e32 v89, v89, v240
	v_lshlrev_b32_e32 v239, 16, v171
	v_and_b32_e32 v240, 0xffff0000, v171
	v_add_f32_e32 v90, v90, v239
	v_add_f32_e32 v91, v91, v240
	v_lshlrev_b32_e32 v239, 16, v172
	v_and_b32_e32 v240, 0xffff0000, v172
	v_add_f32_e32 v84, v84, v239
	v_add_f32_e32 v85, v85, v240
	v_lshlrev_b32_e32 v239, 16, v173
	v_and_b32_e32 v240, 0xffff0000, v173
	v_add_f32_e32 v86, v86, v239
	v_add_f32_e32 v87, v87, v240
	v_cvt_pk_bf16_f32 v170, v88, v89
	v_cvt_pk_bf16_f32 v171, v90, v91
	v_cvt_pk_bf16_f32 v172, v84, v85
	v_cvt_pk_bf16_f32 v173, v86, v87
	global_store_dwordx4 v144, v[170:173], s[8:9] offset:256
	v_mul_f32_e32 v239, v89, v89
	v_mul_f32_e32 v240, v91, v91
	v_fmac_f32_e32 v239, v88, v88
	v_fmac_f32_e32 v240, v90, v90
	v_add_f32_e32 v239, v239, v240
	v_mul_f32_e32 v240, v85, v85
	v_fmac_f32_e32 v240, v84, v84
	v_add_f32_e32 v239, v240, v239
	v_mul_f32_e32 v240, v87, v87
	v_fmac_f32_e32 v240, v86, v86
	v_add_f32_e32 v88, v240, v239
	v_add_f32_e32 v96, v96, v88
	s_waitcnt vmcnt(14)
	v_lshlrev_b32_e32 v239, 16, v174
	v_and_b32_e32 v240, 0xffff0000, v174
	v_add_f32_e32 v80, v80, v239
	v_add_f32_e32 v81, v81, v240
	v_lshlrev_b32_e32 v239, 16, v175
	v_and_b32_e32 v240, 0xffff0000, v175
	v_add_f32_e32 v82, v82, v239
	v_add_f32_e32 v83, v83, v240
	v_lshlrev_b32_e32 v239, 16, v176
	v_and_b32_e32 v240, 0xffff0000, v176
	v_add_f32_e32 v76, v76, v239
	v_add_f32_e32 v77, v77, v240
	v_lshlrev_b32_e32 v239, 16, v177
	v_and_b32_e32 v240, 0xffff0000, v177
	v_add_f32_e32 v78, v78, v239
	v_add_f32_e32 v79, v79, v240
	v_cvt_pk_bf16_f32 v174, v80, v81
	v_cvt_pk_bf16_f32 v175, v82, v83
	v_cvt_pk_bf16_f32 v176, v76, v77
	v_cvt_pk_bf16_f32 v177, v78, v79
	global_store_dwordx4 v145, v[174:177], s[8:9]
	v_mul_f32_e32 v239, v81, v81
	v_mul_f32_e32 v240, v83, v83
	v_fmac_f32_e32 v239, v80, v80
	v_fmac_f32_e32 v240, v82, v82
	v_add_f32_e32 v239, v239, v240
	v_mul_f32_e32 v240, v77, v77
	v_fmac_f32_e32 v240, v76, v76
	v_add_f32_e32 v239, v240, v239
	v_mul_f32_e32 v240, v79, v79
	v_fmac_f32_e32 v240, v78, v78
	v_add_f32_e32 v80, v240, v239
	v_lshlrev_b32_e32 v239, 16, v178
	v_and_b32_e32 v240, 0xffff0000, v178
	v_add_f32_e32 v72, v72, v239
	v_add_f32_e32 v73, v73, v240
	v_lshlrev_b32_e32 v239, 16, v179
	v_and_b32_e32 v240, 0xffff0000, v179
	v_add_f32_e32 v74, v74, v239
	v_add_f32_e32 v75, v75, v240
	v_lshlrev_b32_e32 v239, 16, v180
	v_and_b32_e32 v240, 0xffff0000, v180
	v_add_f32_e32 v68, v68, v239
	v_add_f32_e32 v69, v69, v240
	v_lshlrev_b32_e32 v239, 16, v181
	v_and_b32_e32 v240, 0xffff0000, v181
	v_add_f32_e32 v70, v70, v239
	v_add_f32_e32 v71, v71, v240
	v_cvt_pk_bf16_f32 v178, v72, v73
	v_cvt_pk_bf16_f32 v179, v74, v75
	v_cvt_pk_bf16_f32 v180, v68, v69
	v_cvt_pk_bf16_f32 v181, v70, v71
	global_store_dwordx4 v145, v[178:181], s[8:9] offset:256
	v_mul_f32_e32 v239, v73, v73
	v_mul_f32_e32 v240, v75, v75
	v_fmac_f32_e32 v239, v72, v72
	v_fmac_f32_e32 v240, v74, v74
	v_add_f32_e32 v239, v239, v240
	v_mul_f32_e32 v240, v69, v69
	v_fmac_f32_e32 v240, v68, v68
	v_add_f32_e32 v239, v240, v239
	v_mul_f32_e32 v240, v71, v71
	v_fmac_f32_e32 v240, v70, v70
	v_add_f32_e32 v72, v240, v239
	v_add_f32_e32 v80, v80, v72
	s_waitcnt vmcnt(14)
	v_lshlrev_b32_e32 v239, 16, v182
	v_and_b32_e32 v240, 0xffff0000, v182
	v_add_f32_e32 v64, v64, v239
	v_add_f32_e32 v65, v65, v240
	v_lshlrev_b32_e32 v239, 16, v183
	v_and_b32_e32 v240, 0xffff0000, v183
	v_add_f32_e32 v66, v66, v239
	v_add_f32_e32 v67, v67, v240
	v_lshlrev_b32_e32 v239, 16, v184
	v_and_b32_e32 v240, 0xffff0000, v184
	v_add_f32_e32 v60, v60, v239
	v_add_f32_e32 v61, v61, v240
	v_lshlrev_b32_e32 v239, 16, v185
	v_and_b32_e32 v240, 0xffff0000, v185
	v_add_f32_e32 v62, v62, v239
	v_add_f32_e32 v63, v63, v240
	v_cvt_pk_bf16_f32 v182, v64, v65
	v_cvt_pk_bf16_f32 v183, v66, v67
	v_cvt_pk_bf16_f32 v184, v60, v61
	v_cvt_pk_bf16_f32 v185, v62, v63
	global_store_dwordx4 v204, v[182:185], s[8:9]
	v_mul_f32_e32 v239, v65, v65
	v_mul_f32_e32 v240, v67, v67
	v_fmac_f32_e32 v239, v64, v64
	v_fmac_f32_e32 v240, v66, v66
	v_add_f32_e32 v239, v239, v240
	v_mul_f32_e32 v240, v61, v61
	v_fmac_f32_e32 v240, v60, v60
	v_add_f32_e32 v239, v240, v239
	v_mul_f32_e32 v240, v63, v63
	v_fmac_f32_e32 v240, v62, v62
	v_add_f32_e32 v64, v240, v239
	v_lshlrev_b32_e32 v239, 16, v186
	v_and_b32_e32 v240, 0xffff0000, v186
	v_add_f32_e32 v56, v56, v239
	v_add_f32_e32 v57, v57, v240
	v_lshlrev_b32_e32 v239, 16, v187
	v_and_b32_e32 v240, 0xffff0000, v187
	v_add_f32_e32 v58, v58, v239
	v_add_f32_e32 v59, v59, v240
	v_lshlrev_b32_e32 v239, 16, v188
	v_and_b32_e32 v240, 0xffff0000, v188
	v_add_f32_e32 v52, v52, v239
	v_add_f32_e32 v53, v53, v240
	v_lshlrev_b32_e32 v239, 16, v189
	v_and_b32_e32 v240, 0xffff0000, v189
	v_add_f32_e32 v54, v54, v239
	v_add_f32_e32 v55, v55, v240
	v_cvt_pk_bf16_f32 v186, v56, v57
	v_cvt_pk_bf16_f32 v187, v58, v59
	v_cvt_pk_bf16_f32 v188, v52, v53
	v_cvt_pk_bf16_f32 v189, v54, v55
	global_store_dwordx4 v204, v[186:189], s[8:9] offset:256
	v_mul_f32_e32 v239, v57, v57
	v_mul_f32_e32 v240, v59, v59
	v_fmac_f32_e32 v239, v56, v56
	v_fmac_f32_e32 v240, v58, v58
	v_add_f32_e32 v239, v239, v240
	v_mul_f32_e32 v240, v53, v53
	v_fmac_f32_e32 v240, v52, v52
	v_add_f32_e32 v239, v240, v239
	v_mul_f32_e32 v240, v55, v55
	v_fmac_f32_e32 v240, v54, v54
	v_add_f32_e32 v56, v240, v239
	v_add_f32_e32 v64, v64, v56
	s_waitcnt vmcnt(14)
; __device__ __forceinline__ unsigned cvt_pk_bf16(float lo, float hi) { unsigned r; asm volatile("v_cvt_pk_bf16_f32 %0, %1, %2" : "=v"(r) : "v"(lo), "v"(hi)); return r; }
;     __device__ __forceinline__ void operator()(const f32x4 (&acc)[2][2][4][2], const Unit& u, int wr, int wc, int fr, int fq) const {
;     ...
;             for (int m = 0; m < 4; ++m) { const int row = row0 + ai * HALF + m * 16; const size_t off = (size_t)row * 1024 + col0; float part = 0.f;
; #pragma unroll
;                 for (int bj = 0; bj < 2; ++bj) { const u32x4 b = *(const u32x4*)(hb + off + bj * HALF);
;                     f32x4 v0 = acc[ai][bj][m][0], v1 = acc[ai][bj][m][1];
;                     v0[0] += __uint_as_float(b.x << 16); v0[1] += __uint_as_float(b.x & 0xffff0000u); v0[2] += __uint_as_float(b.y << 16); v0[3] += __uint_as_float(b.y & 0xffff0000u);
;                     v1[0] += __uint_as_float(b.z << 16); v1[1] += __uint_as_float(b.z & 0xffff0000u); v1[2] += __uint_as_float(b.w << 16); v1[3] += __uint_as_float(b.w & 0xffff0000u);
;                     u32x4 w; w.x = cvt_pk_bf16(v0[0], v0[1]); w.y = cvt_pk_bf16(v0[2], v0[3]); w.z = cvt_pk_bf16(v1[0], v1[1]); w.w = cvt_pk_bf16(v1[2], v1[3]);
;                     *(u32x4*)(hb + off + bj * HALF) = w;
;                     part += (v0[0] * v0[0] + v0[1] * v0[1]) + (v0[2] * v0[2] + v0[3] * v0[3]) + (v1[0] * v1[0] + v1[1] * v1[1]) + (v1[2] * v1[2] + v1[3] * v1[3]); }
	v_lshlrev_b32_e32 v239, 16, v190
	v_and_b32_e32 v240, 0xffff0000, v190
	v_add_f32_e32 v48, v48, v239
	v_add_f32_e32 v49, v49, v240
	v_lshlrev_b32_e32 v239, 16, v191
	v_and_b32_e32 v240, 0xffff0000, v191
	v_add_f32_e32 v50, v50, v239
	v_add_f32_e32 v51, v51, v240
	v_lshlrev_b32_e32 v239, 16, v192
	v_and_b32_e32 v240, 0xffff0000, v192
	v_add_f32_e32 v44, v44, v239
	v_add_f32_e32 v45, v45, v240
	v_lshlrev_b32_e32 v239, 16, v193
	v_and_b32_e32 v240, 0xffff0000, v193
	v_add_f32_e32 v46, v46, v239
	v_add_f32_e32 v47, v47, v240
	v_cvt_pk_bf16_f32 v190, v48, v49
	v_cvt_pk_bf16_f32 v191, v50, v51
	v_cvt_pk_bf16_f32 v192, v44, v45
	v_cvt_pk_bf16_f32 v193, v46, v47
	global_store_dwordx4 v205, v[190:193], s[8:9]
	v_mul_f32_e32 v239, v49, v49
	v_mul_f32_e32 v240, v51, v51
	v_fmac_f32_e32 v239, v48, v48
	v_fmac_f32_e32 v240, v50, v50
	v_add_f32_e32 v239, v239, v240
	v_mul_f32_e32 v240, v45, v45
	v_fmac_f32_e32 v240, v44, v44
	v_add_f32_e32 v239, v240, v239
	v_mul_f32_e32 v240, v47, v47
	v_fmac_f32_e32 v240, v46, v46
	v_add_f32_e32 v48, v240, v239
	v_lshlrev_b32_e32 v239, 16, v194
	v_and_b32_e32 v240, 0xffff0000, v194
	v_add_f32_e32 v40, v40, v239
	v_add_f32_e32 v41, v41, v240
	v_lshlrev_b32_e32 v239, 16, v195
	v_and_b32_e32 v240, 0xffff0000, v195
	v_add_f32_e32 v42, v42, v239
	v_add_f32_e32 v43, v43, v240
	v_lshlrev_b32_e32 v239, 16, v196
	v_and_b32_e32 v240, 0xffff0000, v196
	v_add_f32_e32 v36, v36, v239
	v_add_f32_e32 v37, v37, v240
	v_lshlrev_b32_e32 v239, 16, v197
	v_and_b32_e32 v240, 0xffff0000, v197
	v_add_f32_e32 v38, v38, v239
	v_add_f32_e32 v39, v39, v240
	v_cvt_pk_bf16_f32 v194, v40, v41
	v_cvt_pk_bf16_f32 v195, v42, v43
	v_cvt_pk_bf16_f32 v196, v36, v37
	v_cvt_pk_bf16_f32 v197, v38, v39
	global_store_dwordx4 v205, v[194:197], s[8:9] offset:256
	v_mul_f32_e32 v239, v41, v41
	v_mul_f32_e32 v240, v43, v43
	v_fmac_f32_e32 v239, v40, v40
	v_fmac_f32_e32 v240, v42, v42
	v_add_f32_e32 v239, v239, v240
	v_mul_f32_e32 v240, v37, v37
	v_fmac_f32_e32 v240, v36, v36
	v_add_f32_e32 v239, v240, v239
	v_mul_f32_e32 v240, v39, v39
	v_fmac_f32_e32 v240, v38, v38
	v_add_f32_e32 v40, v240, v239
	v_add_f32_e32 v48, v48, v40
	s_waitcnt vmcnt(14)
	v_lshlrev_b32_e32 v239, 16, v220
	v_and_b32_e32 v240, 0xffff0000, v220
	v_add_f32_e32 v32, v32, v239
	v_add_f32_e32 v33, v33, v240
	v_lshlrev_b32_e32 v239, 16, v221
	v_and_b32_e32 v240, 0xffff0000, v221
	v_add_f32_e32 v34, v34, v239
	v_add_f32_e32 v35, v35, v240
	v_lshlrev_b32_e32 v239, 16, v222
	v_and_b32_e32 v240, 0xffff0000, v222
	v_add_f32_e32 v28, v28, v239
	v_add_f32_e32 v29, v29, v240
	v_lshlrev_b32_e32 v239, 16, v223
	v_and_b32_e32 v240, 0xffff0000, v223
	v_add_f32_e32 v30, v30, v239
	v_add_f32_e32 v31, v31, v240
	v_cvt_pk_bf16_f32 v220, v32, v33
	v_cvt_pk_bf16_f32 v221, v34, v35
	v_cvt_pk_bf16_f32 v222, v28, v29
	v_cvt_pk_bf16_f32 v223, v30, v31
	global_store_dwordx4 v206, v[220:223], s[8:9]
	v_mul_f32_e32 v239, v33, v33
	v_mul_f32_e32 v240, v35, v35
	v_fmac_f32_e32 v239, v32, v32
	v_fmac_f32_e32 v240, v34, v34
	v_add_f32_e32 v239, v239, v240
	v_mul_f32_e32 v240, v29, v29
	v_fmac_f32_e32 v240, v28, v28
	v_add_f32_e32 v239, v240, v239
	v_mul_f32_e32 v240, v31, v31
	v_fmac_f32_e32 v240, v30, v30
	v_add_f32_e32 v32, v240, v239
	v_lshlrev_b32_e32 v239, 16, v224
	v_and_b32_e32 v240, 0xffff0000, v224
	v_add_f32_e32 v24, v24, v239
	v_add_f32_e32 v25, v25, v240
	v_lshlrev_b32_e32 v239, 16, v225
	v_and_b32_e32 v240, 0xffff0000, v225
	v_add_f32_e32 v26, v26, v239
	v_add_f32_e32 v27, v27, v240
	v_lshlrev_b32_e32 v239, 16, v226
	v_and_b32_e32 v240, 0xffff0000, v226
	v_add_f32_e32 v20, v20, v239
	v_add_f32_e32 v21, v21, v240
	v_lshlrev_b32_e32 v239, 16, v227
	v_and_b32_e32 v240, 0xffff0000, v227
	v_add_f32_e32 v22, v22, v239
	v_add_f32_e32 v23, v23, v240
	v_cvt_pk_bf16_f32 v224, v24, v25
	v_cvt_pk_bf16_f32 v225, v26, v27
	v_cvt_pk_bf16_f32 v226, v20, v21
	v_cvt_pk_bf16_f32 v227, v22, v23
	global_store_dwordx4 v206, v[224:227], s[8:9] offset:256
	v_mul_f32_e32 v239, v25, v25
	v_mul_f32_e32 v240, v27, v27
	v_fmac_f32_e32 v239, v24, v24
	v_fmac_f32_e32 v240, v26, v26
	v_add_f32_e32 v239, v239, v240
	v_mul_f32_e32 v240, v21, v21
	v_fmac_f32_e32 v240, v20, v20
	v_add_f32_e32 v239, v240, v239
	v_mul_f32_e32 v240, v23, v23
	v_fmac_f32_e32 v240, v22, v22
	v_add_f32_e32 v24, v240, v239
	v_add_f32_e32 v32, v32, v24
	s_waitcnt vmcnt(14)
; __device__ __forceinline__ unsigned cvt_pk_bf16(float lo, float hi) { unsigned r; asm volatile("v_cvt_pk_bf16_f32 %0, %1, %2" : "=v"(r) : "v"(lo), "v"(hi)); return r; }
;     __device__ __forceinline__ void operator()(const f32x4 (&acc)[2][2][4][2], const Unit& u, int wr, int wc, int fr, int fq) const {
;     ...
;                 for (int bj = 0; bj < 2; ++bj) { const u32x4 b = *(const u32x4*)(hb + off + bj * HALF);
;                     f32x4 v0 = acc[ai][bj][m][0], v1 = acc[ai][bj][m][1];
;                     v0[0] += __uint_as_float(b.x << 16); v0[1] += __uint_as_float(b.x & 0xffff0000u); v0[2] += __uint_as_float(b.y << 16); v0[3] += __uint_as_float(b.y & 0xffff0000u);
;                     v1[0] += __uint_as_float(b.z << 16); v1[1] += __uint_as_float(b.z & 0xffff0000u); v1[2] += __uint_as_float(b.w << 16); v1[3] += __uint_as_float(b.w & 0xffff0000u);
;                     u32x4 w; w.x = cvt_pk_bf16(v0[0], v0[1]); w.y = cvt_pk_bf16(v0[2], v0[3]); w.z = cvt_pk_bf16(v1[0], v1[1]); w.w = cvt_pk_bf16(v1[2], v1[3]);
;                     *(u32x4*)(hb + off + bj * HALF) = w;
;                     part += (v0[0] * v0[0] + v0[1] * v0[1]) + (v0[2] * v0[2] + v0[3] * v0[3]) + (v1[0] * v1[0] + v1[1] * v1[1]) + (v1[2] * v1[2] + v1[3] * v1[3]); }
;                 part += __shfl_xor(part, 16); part += __shfl_xor(part, 32);
;                 if (fq == 0) ssq[(size_t)row * 16 + u.pn * 4 + wc] = part; }
	v_lshlrev_b32_e32 v239, 16, v228
	v_and_b32_e32 v240, 0xffff0000, v228
	v_add_f32_e32 v16, v16, v239
	v_add_f32_e32 v17, v17, v240
	v_lshlrev_b32_e32 v239, 16, v229
	v_and_b32_e32 v240, 0xffff0000, v229
	v_add_f32_e32 v18, v18, v239
	v_add_f32_e32 v19, v19, v240
	v_lshlrev_b32_e32 v239, 16, v230
	v_and_b32_e32 v240, 0xffff0000, v230
	v_add_f32_e32 v12, v12, v239
	v_add_f32_e32 v13, v13, v240
	v_lshlrev_b32_e32 v239, 16, v231
	v_and_b32_e32 v240, 0xffff0000, v231
	v_add_f32_e32 v14, v14, v239
	v_add_f32_e32 v15, v15, v240
	v_cvt_pk_bf16_f32 v228, v16, v17
	v_cvt_pk_bf16_f32 v229, v18, v19
	v_cvt_pk_bf16_f32 v230, v12, v13
	v_cvt_pk_bf16_f32 v231, v14, v15
	global_store_dwordx4 v207, v[228:231], s[8:9]
	v_mul_f32_e32 v239, v17, v17
	v_mul_f32_e32 v240, v19, v19
	v_fmac_f32_e32 v239, v16, v16
	v_fmac_f32_e32 v240, v18, v18
	v_add_f32_e32 v239, v239, v240
	v_mul_f32_e32 v240, v13, v13
	v_fmac_f32_e32 v240, v12, v12
	v_add_f32_e32 v239, v240, v239
	v_mul_f32_e32 v240, v15, v15
	v_fmac_f32_e32 v240, v14, v14
	v_add_f32_e32 v16, v240, v239
	v_lshlrev_b32_e32 v239, 16, v232
	v_and_b32_e32 v240, 0xffff0000, v232
	v_add_f32_e32 v8, v8, v239
	v_add_f32_e32 v9, v9, v240
	v_lshlrev_b32_e32 v239, 16, v233
	v_and_b32_e32 v240, 0xffff0000, v233
	v_add_f32_e32 v10, v10, v239
	v_add_f32_e32 v11, v11, v240
	v_lshlrev_b32_e32 v239, 16, v234
	v_and_b32_e32 v240, 0xffff0000, v234
	v_add_f32_e32 v4, v4, v239
	v_add_f32_e32 v5, v5, v240
	v_lshlrev_b32_e32 v239, 16, v235
	v_and_b32_e32 v240, 0xffff0000, v235
	v_add_f32_e32 v6, v6, v239
	v_add_f32_e32 v7, v7, v240
	v_cvt_pk_bf16_f32 v232, v8, v9
	v_cvt_pk_bf16_f32 v233, v10, v11
	v_cvt_pk_bf16_f32 v234, v4, v5
	v_cvt_pk_bf16_f32 v235, v6, v7
	global_store_dwordx4 v207, v[232:235], s[8:9] offset:256
	v_mul_f32_e32 v239, v9, v9
	v_mul_f32_e32 v240, v11, v11
	v_fmac_f32_e32 v239, v8, v8
	v_fmac_f32_e32 v240, v10, v10
	v_add_f32_e32 v239, v239, v240
	v_mul_f32_e32 v240, v5, v5
	v_fmac_f32_e32 v240, v4, v4
	v_add_f32_e32 v239, v240, v239
	v_mul_f32_e32 v240, v7, v7
	v_fmac_f32_e32 v240, v6, v6
	v_add_f32_e32 v8, v240, v239
	v_add_f32_e32 v16, v16, v8
	ds_bpermute_b32 v129, v236, v128
	ds_bpermute_b32 v113, v236, v112
	ds_bpermute_b32 v97, v236, v96
	ds_bpermute_b32 v81, v236, v80
	ds_bpermute_b32 v65, v236, v64
	ds_bpermute_b32 v49, v236, v48
	ds_bpermute_b32 v33, v236, v32
	ds_bpermute_b32 v17, v236, v16
	s_waitcnt lgkmcnt(7)
	v_add_f32_e32 v128, v128, v129
	s_waitcnt lgkmcnt(6)
	v_add_f32_e32 v112, v112, v113
	s_waitcnt lgkmcnt(5)
	v_add_f32_e32 v96, v96, v97
	s_waitcnt lgkmcnt(4)
	v_add_f32_e32 v80, v80, v81
	s_waitcnt lgkmcnt(3)
	v_add_f32_e32 v64, v64, v65
	s_waitcnt lgkmcnt(2)
	v_add_f32_e32 v48, v48, v49
	s_waitcnt lgkmcnt(1)
	v_add_f32_e32 v32, v32, v33
	s_waitcnt lgkmcnt(0)
	v_add_f32_e32 v16, v16, v17
	ds_bpermute_b32 v129, v237, v128
	ds_bpermute_b32 v113, v237, v112
	ds_bpermute_b32 v97, v237, v96
	ds_bpermute_b32 v81, v237, v80
	ds_bpermute_b32 v65, v237, v64
	ds_bpermute_b32 v49, v237, v48
	ds_bpermute_b32 v33, v237, v32
	ds_bpermute_b32 v17, v237, v16
	s_waitcnt lgkmcnt(7)
	v_add_f32_e32 v128, v128, v129
	s_waitcnt lgkmcnt(6)
	v_add_f32_e32 v112, v112, v113
	s_waitcnt lgkmcnt(5)
	v_add_f32_e32 v96, v96, v97
	s_waitcnt lgkmcnt(4)
	v_add_f32_e32 v80, v80, v81
	s_waitcnt lgkmcnt(3)
	v_add_f32_e32 v64, v64, v65
	s_waitcnt lgkmcnt(2)
	v_add_f32_e32 v48, v48, v49
	s_waitcnt lgkmcnt(1)
	v_add_f32_e32 v32, v32, v33
	s_waitcnt lgkmcnt(0)
	v_add_f32_e32 v16, v16, v17
	s_lshl_b32 s28, s11, 4
	s_lshl_b32 s84, s43, 2
	s_add_i32 s28, s28, s84
	v_lshl_add_u32 v241, v238, 6, s28
	s_and_saveexec_b64 s[26:27], s[2:3]
	global_store_dword v241, v128, s[20:21]
	global_store_dword v241, v112, s[20:21] offset:1024
	global_store_dword v241, v96, s[20:21] offset:2048
	global_store_dword v241, v80, s[20:21] offset:3072
	v_add_u32_e32 v241, 0x2000, v241
	global_store_dword v241, v64, s[20:21]
	global_store_dword v241, v48, s[20:21] offset:1024
	global_store_dword v241, v32, s[20:21] offset:2048
	global_store_dword v241, v16, s[20:21] offset:3072
	s_or_b64 exec, exec, s[26:27]
	s_lshl_b32 s28, s11, 2
	s_ashr_i32 s29, s28, 31
	s_and_b64 vcc, exec, s[4:5]
	s_mov_b64 s[4:5], -1
	s_cbranch_vccnz .LBB0_626
	s_andn2_b64 vcc, exec, s[18:19]
	s_cbranch_vccnz .LBB0_625
	s_barrier
	s_branch .LBB0_625
